# P2: log-decay table G relocated from the Tf/Zw region to the TW/AD regions (free between E2 and the score stage): the barrier in front of the G write is gone (one workgroup barrier fewer per item)
# speedup vs baseline: 1.0014x; 1.0014x over previous
; __device__ void rwkv_prep_item(const Params& p, char* lds_, int item, PrepRaw& raw, int next_item) {
;   char* lds = lds_ + 256;
;   const int tid = threadIdx.x, lane = tid & 63, wave = tid >> 6;
;   const int b = item >> 9, hd = (item >> 6) & 7, c = item & 63;
;   constexpr int RB = 64 * LD * 2;
;   u16* At = (u16*)(lds + 0 * RB);  u16* Bt = (u16*)(lds + 1 * RB);  u16* Kt = (u16*)(lds + 2 * RB);  u16* Rt = (u16*)(lds + 3 * RB);
;   u16* AT = (u16*)(lds + 4 * RB);  u16* BT = (u16*)(lds + 5 * RB);  u16* KT = (u16*)(lds + 6 * RB);  u16* VT = (u16*)(lds + 7 * RB);
;   u16* LAK = (u16*)(lds + 8 * RB); u16* MRB = (u16*)(lds + 9 * RB); u16* MRK = (u16*)(lds + 10 * RB); u16* TB = (u16*)(lds + 11 * RB);
;   float* Tf = (float*)(lds + 12 * RB);
;   float* gC = (float*)(lds + 12 * RB + 64 * 68 * 4);
;   float* Za = (float*)(lds + 12 * RB + 64 * 68 * 4 + 256);
;   u16* X1T = At; u16* WT = Bt; u16* U0T = Kt;
;   u16* TW = LAK; u16* AD = MRB; u16* DUs = MRK; u16* IUs = TB;
;   float* Zw = Tf; float* G = Tf;
;   const int t = tid >> 3, cg8 = (tid & 7) * 8;
;   const int pos = c * 64 + t;
;   const size_t tokrow = (size_t)b * SEQ + pos;
;   const u16* prow = p.PB + tokrow * PBW;
;   const bool hasprev = pos > 0;
;   float rr[8], kk_[8], vv[8];
.LBB0_273:
.LBB0_274:
	v_bfe_u32 v115, v223, 4, 2
	s_andn2_b64 vcc, exec, s[4:5]
	v_lshrrev_b32_e32 v158, 6, v223
	v_and_b32_e32 v174, 15, v223
	v_lshrrev_b32_e32 v175, 1, v223
	v_lshlrev_b32_e32 v114, 2, v115
	s_cbranch_vccnz .LBB0_330
	v_lshlrev_b32_e32 v28, 5, v158
	v_and_or_b32 v30, v28, 32, v174
	v_and_b32_e32 v29, 24, v175
	v_mul_u32_u24_e32 v24, 0x48, v30
	s_add_i32 s5, 0, 0x18d00
	v_and_b32_e32 v26, 0x70, v240
	v_lshlrev_b32_e32 v35, 1, v24
	v_or_b32_e32 v36, 32, v29
	v_or_b32_e32 v27, v26, v174
	v_lshlrev_b32_e32 v31, 1, v29
	v_lshlrev_b32_e32 v37, 1, v36
	v_add_u32_e32 v24, s5, v35
	v_add_u32_e32 v167, v24, v31
	v_add_u32_e32 v168, v24, v37
	v_mul_u32_u24_e32 v24, 0x44, v27
	v_bfe_u32 v25, v223, 6, 1
	v_lshlrev_b32_e32 v24, 2, v24
	s_add_i32 s15, 0, 0x1b100
	s_add_i32 s74, 0, 0x1f600
	v_add_u32_e32 v39, s15, v24
	v_add_u32_e32 v40, s74, v24
	v_lshlrev_b32_e32 v41, 7, v25
	v_and_b32_e32 v24, 48, v223
	v_and_b32_e32 v116, 56, v219
	v_add3_u32 v170, v39, v24, v41
	v_mul_u32_u24_e32 v39, 0x44, v240
	v_add_lshl_u32 v39, v39, v116, 2
	v_add_u32_e32 v172, s15, v39
	v_add_u32_e32 v173, s74, v39
	v_add_u32_e32 v39, 16, v39
	v_add_u32_e32 v176, s15, v39
	v_add_u32_e32 v177, s74, v39
	v_mbcnt_hi_u32_b32 v39, -1, v241
	v_add3_u32 v171, v40, v24, v41
	v_and_b32_e32 v41, 64, v39
	v_xor_b32_e32 v40, 1, v39
	v_add_u32_e32 v41, 64, v41
	v_cmp_lt_i32_e32 vcc, v40, v41
	v_mul_u32_u24_e32 v22, 0x48, v240
	v_mov_b32_e32 v242, v241
	v_cndmask_b32_e32 v40, v39, v40, vcc
	v_lshlrev_b32_e32 v178, 2, v40
	v_xor_b32_e32 v40, 2, v39
	v_cmp_lt_i32_e32 vcc, v40, v41
	s_add_i32 s14, 0, 0x12100
	v_lshlrev_b32_e32 v23, 1, v22
	v_cndmask_b32_e32 v40, v39, v40, vcc
	v_lshlrev_b32_e32 v179, 2, v40
	v_xor_b32_e32 v40, 4, v39
	v_cmp_lt_i32_e32 vcc, v40, v41
	v_lshlrev_b32_e32 v22, 1, v116
	s_add_i32 s4, 0, 0x14500
	v_cndmask_b32_e32 v39, v39, v40, vcc
	v_cmp_eq_u32_e32 vcc, 0, v174
	s_add_i32 s10, 0, 0x16900
	v_mul_u32_u24_e32 v47, 0x110, v24
	v_cndmask_b32_e64 v190, 0, 1.0, vcc
	v_cmp_eq_u32_e32 vcc, 1, v174
	v_lshlrev_b32_e32 v48, 2, v24
	v_add3_u32 v117, s14, v23, v22
	v_cndmask_b32_e64 v191, 0, 1.0, vcc
	v_cmp_eq_u32_e32 vcc, 2, v174
	v_cndmask_b32_e64 v253, 0, 1.0, vcc
	v_cmp_eq_u32_e32 vcc, 3, v174
	v_mul_u32_u24_e32 v32, 0x48, v27
	v_cndmask_b32_e64 v254, 0, 1.0, vcc
	v_cmp_eq_u32_e32 vcc, 4, v174
	v_add3_u32 v184, 0, v23, v22
	v_bitop3_b32 v23, v219, v240, 56 bitop3:0x6c
	v_cndmask_b32_e64 v255, 0, 1.0, vcc
	v_cmp_eq_u32_e32 vcc, 5, v174
	v_add3_u32 v189, s15, v47, v48
	v_lshlrev_b32_e32 v47, 2, v174
	v_cndmask_b32_e64 v241, 0, 1.0, vcc
	v_cmp_eq_u32_e32 vcc, 6, v174
	v_or_b32_e32 v48, 16, v28
	v_lshlrev_b32_e32 v120, 6, v25
	v_cndmask_b32_e64 v196, 0, 1.0, vcc
	v_cmp_eq_u32_e32 vcc, 7, v174
	v_lshlrev_b32_e32 v32, 1, v32
	s_movk_i32 s16, 0x110
	v_cndmask_b32_e64 v197, 0, 1.0, vcc
	v_cmp_eq_u32_e32 vcc, 8, v174
	v_mul_u32_u24_e32 v43, 0x90, v116
	v_lshlrev_b32_e32 v23, 1, v23
	v_cndmask_b32_e64 v198, 0, 1.0, vcc
	v_cmp_eq_u32_e32 vcc, 9, v174
	v_or_b32_e32 v49, v48, v174
	v_add3_u32 v211, s15, v120, v47
	v_or_b32_e32 v26, v114, v26
	v_add3_u32 v185, 0, v43, v23
	v_add_u32_e32 v23, 0, v32
	v_cndmask_b32_e64 v199, 0, 1.0, vcc
	v_cmp_eq_u32_e32 vcc, 10, v174
	v_mul_u32_u24_e32 v49, 0x110, v49
	v_lshl_add_u32 v50, v158, 7, s15
	v_or_b32_e32 v28, v28, v115
	v_mul_u32_u24_e32 v52, 0x84, v26
	v_mad_u32_u24 v212, v26, s16, v211
	v_bitop3_b32 v26, v27, v29, 56 bitop3:0x6c
	v_cndmask_b32_e64 v200, 0, 1.0, vcc
	v_cmp_eq_u32_e32 vcc, 11, v174
	v_add3_u32 v207, v50, v49, v114
	v_add_u32_e32 v49, v50, v47
	v_mul_u32_u24_e32 v50, 0x110, v28
	v_mul_u32_u24_e32 v28, 0x440, v158
	v_lshl_add_u32 v213, v26, 1, v23
	v_add_u32_e32 v26, s14, v35
	v_lshlrev_b32_e32 v180, 2, v39
	v_mul_u32_u24_e32 v39, 0x110, v240
	v_lshlrev_b32_e32 v40, 2, v116
	v_add_u32_e32 v43, 0, v35
	v_cndmask_b32_e64 v201, 0, 1.0, vcc
	v_cmp_eq_u32_e32 vcc, 12, v174
	v_add3_u32 v208, s74, v28, v47
	v_or_b32_e32 v28, v48, v114
	v_add_u32_e32 v214, v26, v31
	v_add_u32_e32 v216, v26, v37
	v_bitop3_b32 v26, v30, v29, 40 bitop3:0x6c
	v_add3_u32 v181, s14, v39, v40
	v_lshlrev_b32_e32 v39, 2, v222
	v_cndmask_b32_e64 v202, 0, 1.0, vcc
	v_cmp_eq_u32_e32 vcc, 13, v174
	v_mul_u32_u24_e32 v48, 0x110, v28
	v_bitop3_b32 v28, v27, v36, 56 bitop3:0x6c
	v_lshl_add_u32 v222, v26, 1, v43
	v_or_b32_e32 v26, 16, v30
	v_cndmask_b32_e64 v203, 0, 1.0, vcc
	v_cmp_eq_u32_e32 vcc, 14, v174
	v_lshl_add_u32 v215, v28, 1, v23
	v_mul_u32_u24_e32 v28, 0x48, v26
	s_add_i32 s44, 0, 0x1f500
	v_lshl_or_b32 v46, v25, 1, 1
	v_cndmask_b32_e64 v204, 0, 1.0, vcc
	v_cmp_eq_u32_e32 vcc, 15, v174
	v_lshl_add_u32 v28, v28, 1, 0
	v_bitop3_b32 v29, v26, v29, 56 bitop3:0x6c
	v_bitop3_b32 v26, v26, v36, 56 bitop3:0x6c
	v_lshl_or_b32 v25, v25, 5, v114
	s_cmp_lg_u32 0, -1
	v_cndmask_b32_e64 v205, 0, 1.0, vcc
	v_lshl_add_u32 v224, v29, 1, v28
	v_lshl_add_u32 v226, v26, 1, v28
	v_or_b32_e32 v28, 1, v25
	v_cmp_eq_u32_e32 vcc, v25, v27
	v_add_u32_e32 v41, s14, v39
	s_cselect_b64 s[76:77], -1, 0
	v_mov_b32_e32 v44, s15
	s_add_i32 s15, 0, 0x1fe80
	v_bitop3_b32 v29, v30, v36, 40 bitop3:0x6c
	v_cmp_lt_u32_e64 s[18:19], v28, v27
	v_cndmask_b32_e64 v122, 0, 1.0, vcc
	v_cmp_eq_u32_e32 vcc, v28, v27
	v_or_b32_e32 v28, 3, v25
	v_add_u32_e32 v33, s14, v32
	v_mad_u32_u24 v44, v27, s16, v44
	v_add_u32_e32 v206, v189, v47
	v_add3_u32 v47, s15, v120, v47
	v_add3_u32 v217, s14, v37, v35
	v_lshl_add_u32 v225, v29, 1, v43
	v_cmp_lt_u32_e64 s[14:15], v25, v27
	v_cmp_gt_u32_e64 s[16:17], v25, v27
	v_lshlrev_b32_e32 v29, 2, v25
	v_lshlrev_b32_e32 v26, 1, v25
	v_cndmask_b32_e64 v123, 0, 1.0, vcc
	v_or_b32_e32 v25, 2, v25
	v_cmp_eq_u32_e32 vcc, v28, v27
	s_load_dwordx2 s[78:79], s[0:1], 0xb8
	s_load_dwordx4 s[60:63], s[0:1], 0x18
	s_load_dwordx2 s[80:81], s[0:1], 0x30
	s_load_dwordx4 s[64:67], s[0:1], 0x40
	s_load_dwordx2 s[82:83], s[0:1], 0x50
	s_load_dwordx2 s[84:85], s[0:1], 0xf0
	v_cmp_lt_u32_e64 s[20:21], v25, v27
	v_cmp_gt_u32_e64 s[22:23], v25, v27
	v_cndmask_b32_e64 v125, 0, 1.0, vcc
	v_cmp_eq_u32_e32 vcc, v25, v27
	v_lshl_or_b32 v25, v46, 4, v114
	s_load_dwordx8 s[52:59], s[0:1], 0xd0
	v_mov_b32_e32 v119, 0
	v_lshlrev_b32_e32 v30, 2, v25
	v_or_b32_e32 v118, 0x1800, v40
	v_add_u32_e32 v183, s44, v40
	v_lshl_add_u32 v228, v27, 2, s44
	v_add_u32_e32 v229, v44, v29
	v_cmp_lt_u32_e64 s[24:25], v28, v27
	v_cmp_gt_u32_e64 s[26:27], v28, v27
	v_cndmask_b32_e64 v124, 0, 1.0, vcc
	v_add_u32_e32 v234, s44, v29
	v_or_b32_e32 v29, 1, v25
	v_lshlrev_b32_e32 v28, 1, v25
	v_cmp_eq_u32_e32 vcc, v25, v27
	v_add_u32_e32 v243, s44, v30
	s_waitcnt lgkmcnt(0)
; __device__ void rwkv_prep_item(const Params& p, char* lds_, int item, PrepRaw& raw, int next_item) {
;     ...
;   float rr[8], kk_[8], vv[8];
;   f32x4 pdb[2], pib[2], pkk[2], pka[2], prk[2];
;   {
;     const int cbp = hd * 64 + cg8;
; #pragma unroll
;     for (int q = 0; q < 2; ++q) {
;       pdb[q] = *(const f32x4*)(p.decay_bias + cbp + 4 * q); pib[q] = *(const f32x4*)(p.iclr_bias + cbp + 4 * q);
;       pkk[q] = *(const f32x4*)(p.k_k + cbp + 4 * q); pka[q] = *(const f32x4*)(p.k_a + cbp + 4 * q); prk[q] = *(const f32x4*)(p.r_k + cbp + 4 * q);
;     }
;   }
;     ...
;     *(u32x4*)(DUs + t * LD + cg8) = *(const u32x4*)(p.DUt + (size_t)(hd * 64 + t) * 64 + cg8);
;     *(u32x4*)(IUs + t * LD + cg8) = *(const u32x4*)(p.IUt + (size_t)(hd * 64 + t) * 64 + cg8);
	v_lshl_add_u64 v[130:131], s[60:61], 0, v[118:119]
	v_or_b32_e32 v118, 0x1900, v40
	s_load_dwordx4 s[44:47], s[0:1], 0x128
	v_add_u32_e32 v38, s4, v32
	v_add_u32_e32 v187, v23, v31
	v_lshl_add_u32 v221, v115, 3, v23
	v_add_u32_e32 v233, v23, v26
	v_add_u32_e32 v239, v23, v28
	v_cndmask_b32_e64 v126, 0, 1.0, vcc
	v_cmp_eq_u32_e32 vcc, v29, v27
	v_or_b32_e32 v23, 3, v25
	v_lshl_add_u64 v[132:133], s[60:61], 0, v[118:119]
	v_lshlrev_b32_e32 v118, 7, v240
	v_add_u32_e32 v162, v33, v31
	v_add_u32_e32 v34, s10, v31
	v_add_u32_e32 v166, v38, v31
	v_add_u32_e32 v188, v43, v31
	v_add_u32_e32 v235, v44, v30
	v_cndmask_b32_e64 v127, 0, 1.0, vcc
	v_cmp_lt_u32_e64 s[40:41], v23, v27
	v_cmp_gt_u32_e64 s[42:43], v23, v27
	v_cmp_eq_u32_e32 vcc, v23, v27
	v_mov_b32_e32 v23, v119
	v_lshl_add_u64 v[30:31], s[84:85], 0, v[118:119]
	v_lshlrev_b32_e32 v118, 7, v27
	v_cmp_lt_u32_e64 s[28:29], v25, v27
	v_cmp_gt_u32_e64 s[30:31], v25, v27
	v_or_b32_e32 v25, 2, v25
	v_lshl_add_u64 v[134:135], s[52:53], 0, v[22:23]
	v_lshl_add_u64 v[136:137], s[54:55], 0, v[22:23]
	v_lshl_add_u64 v[138:139], v[30:31], 0, v[22:23]
	v_lshl_add_u64 v[22:23], s[56:57], 0, v[118:119]
	v_mov_b32_e32 v121, v119
	v_cmp_lt_u32_e64 s[36:37], v25, v27
	v_cmp_gt_u32_e64 s[38:39], v25, v27
	v_cndmask_b32_e64 v129, 0, 1.0, vcc
	v_cmp_eq_u32_e32 vcc, v25, v27
	v_lshl_add_u64 v[22:23], v[22:23], 0, v[120:121]
	v_mov_b32_e32 v25, v119
	v_cmp_lt_u32_e64 s[34:35], v29, v27
	v_lshl_add_u64 v[140:141], v[22:23], 0, v[24:25]
	s_waitcnt lgkmcnt(0)
	v_lshl_add_u64 v[22:23], s[44:45], 0, v[118:119]
	v_mov_b32_e32 v27, v119
	v_mov_b32_e32 v29, v119
	v_add_u32_e32 v163, v34, v35
	v_add3_u32 v164, s10, v35, v37
	v_add3_u32 v165, s10, v37, v35
	v_add3_u32 v169, s5, v37, v35
	v_mul_u32_u24_e32 v42, 0x880, v158
	v_add_u32_e32 v45, s10, v32
	s_movk_i32 s10, 0x80
	v_mul_u32_u24_e32 v51, 0x44, v115
	s_movk_i32 s12, 0x100
	v_mul_u32_u24_e32 v53, 0x84, v115
	v_lshlrev_b32_e32 v35, 5, v46
	v_lshl_add_u64 v[142:143], v[22:23], 0, v[26:27]
	v_lshl_add_u64 v[24:25], s[58:59], 0, v[118:119]
	v_lshl_add_u64 v[30:31], s[46:47], 0, v[118:119]
	v_lshl_add_u64 v[148:149], v[22:23], 0, v[28:29]
	v_add_u32_e32 v22, -1, v158
	v_bfe_u32 v121, v223, 6, 3
	s_mov_b32 s75, 0
	v_lshl_add_u32 v182, v223, 2, s74
	v_cmp_gt_u32_e64 s[4:5], 64, v223
	v_cmp_lt_u32_e64 s[6:7], 63, v223
	v_cmp_eq_u32_e64 s[8:9], 63, v240
	v_add_u32_e32 v186, 0xfd00, v185
	v_cmp_gt_u32_e64 s[10:11], s10, v223
	v_mul_u32_u24_e32 v209, 0x110, v115
	v_cmp_gt_u32_e64 s[12:13], s12, v223
	v_add_u32_e32 v210, v44, v114
	v_add_u32_e32 v227, v34, v32
	v_add_u32_e32 v230, v33, v26
	v_add_u32_e32 v231, v38, v26
	v_add_u32_e32 v232, v45, v26
	v_add_u32_e32 v236, v33, v28
	v_add_u32_e32 v237, v38, v28
	v_add_u32_e32 v238, v45, v28
	v_cndmask_b32_e64 v128, 0, 1.0, vcc
	v_lshl_add_u64 v[144:145], v[24:25], 0, v[26:27]
	v_lshl_add_u64 v[146:147], v[30:31], 0, v[26:27]
	v_lshl_add_u64 v[150:151], v[24:25], 0, v[28:29]
	v_lshl_add_u64 v[152:153], v[30:31], 0, v[28:29]
	v_cmp_lt_u32_e64 s[44:45], 6, v22
	v_and_b32_e32 v244, 8, v158
	v_cmp_ne_u32_e64 s[46:47], 0, v121
	v_add_u32_e32 v245, s74, v39
	s_movk_i32 s53, 0xd00
	s_mov_b32 s52, 0xbf1b4598
	v_add_u32_e32 v246, v49, v50
	v_add_u32_e32 v247, v208, v51
	v_add_u32_e32 v248, v49, v48
	v_add_u32_e32 v249, v47, v52
	v_add_u32_e32 v250, v47, v53
	v_add_u32_e32 v251, v221, v35
	v_add_u32_e32 v252, v41, v42
	s_mov_b32 s54, s2
	global_load_dwordx4 v[200:203], v[132:133], off
	s_and_b32 s94, s2, 0x1c0
	v_add_lshl_u32 v196, s94, v240, 7
	v_mov_b32_e32 v197, 0
	v_mov_b64_e32 v[158:159], v[196:197]
	v_lshl_add_u64 v[196:197], v[136:137], 0, v[196:197]
	global_load_dwordx4 v[196:199], v[196:197], off
	v_lshl_add_u64 v[158:159], v[134:135], 0, v[158:159]
	global_load_dwordx4 v[158:161], v[158:159], off
	s_and_b32 s94, s2, 0x1c0
	s_lshl_b32 s94, s94, 2
	v_mov_b32_e32 v25, s94
	s_add_i32 s94, s2, s50
	s_and_b32 s94, s94, 0x1c0
	s_lshl_b32 s94, s94, 2
	v_mov_b32_e32 v26, s94
	v_lshrrev_b32_e32 v22, 4, v223
	v_and_b32_e32 v23, 15, v223
	v_cmp_lt_u32_e32 vcc, 4, v22
	s_nop 1
	v_cndmask_b32_e32 v25, v25, v26, vcc
	v_cndmask_b32_e64 v24, 0, 5, vcc
	v_sub_u32_e32 v22, v22, v24
	v_lshl_add_u32 v24, v22, 11, v25
	v_lshlrev_b32_e32 v26, 8, v22
	v_add_u32_e32 v26, 0x1500, v26
	v_cmp_gt_u32_e32 vcc, 3, v22
	s_nop 1
	v_cndmask_b32_e32 v24, v26, v24, vcc
	v_lshl_add_u32 v24, v23, 4, v24
	v_lshlrev_b32_e32 v23, 4, v223
	v_add_u32_e32 v23, 0x23a00, v23
	v_cmp_gt_u32_e32 vcc, 0xa0, v223
	s_and_saveexec_b64 s[94:95], vcc
	global_load_dwordx4 v[26:29], v24, s[60:61]
	s_waitcnt vmcnt(0)
	ds_write_b128 v23, v[26:29]
	s_waitcnt lgkmcnt(0)
	s_or_b64 exec, exec, s[94:95]
	s_branch .LBB0_277
; __device__ __forceinline__ unsigned pk2(float lo, float hi) { f32x2_t v = {lo, hi}; bf16x2_t b = __builtin_convertvector(v, bf16x2_t); return __builtin_bit_cast(unsigned, b); }
; __device__ void rwkv_prep_item(const Params& p, char* lds_, int item, PrepRaw& raw, int next_item) {
;     ...
;     {
;       const float* tr = Tf + t * 68 + cg8;
;       u32x4 w; w.x = pk2(tr[0], tr[1]); w.y = pk2(tr[2], tr[3]); w.z = pk2(tr[4], tr[5]); w.w = pk2(tr[6], tr[7]);
;       *(u32x4*)(TB + t * LD + cg8) = w;
;     }
;   }
;   __syncthreads();
;   {
;     f32x4 a1[2], a2[2]; zero2(a1); zero2(a2);
;     mm_nt<true, false>(VT, LAK, a1, wave, lane);
;     mm_nt<true, false>(AT, TB, a2, wave, lane);
; #pragma unroll
;     for (int jj = 0; jj < 2; ++jj) {
;       const int j0 = (jt0 + jj) * 16 + 4 * mg;
;       u32x2 w;
;       w.x = pk2(a1[jj][0], a1[jj][1]); w.y = pk2(a1[jj][2], a1[jj][3]); *(u32x2*)(X1T + mi * LD + j0) = w;
;       w.x = pk2(a2[jj][0], a2[jj][1]); w.y = pk2(a2[jj][2], a2[jj][3]); *(u32x2*)(WT + mi * LD + j0) = w;
;     }
;   }
;   __syncthreads();
;   {
;     f32x4 a1[2]; zero2(a1);
;     mm_nt(X1T, TB, a1, wave, lane);
; #pragma unroll
;     for (int jj = 0; jj < 2; ++jj) {
;       const int j0 = (jt0 + jj) * 16 + 4 * mg;
;       u32x2 w; w.x = pk2(a1[jj][0], a1[jj][1]); w.y = pk2(a1[jj][2], a1[jj][3]); *(u32x2*)(U0T + mi * LD + j0) = w;
;     }
;   }
.LBB0_276:
	s_or_b64 exec, exec, s[58:59]
	s_waitcnt lgkmcnt(0)
	s_barrier
	s_nop 3
	ds_read_b128 v[18:21], v172
	ds_read_b128 v[22:25], v172 offset:16
	s_lshl_b64 s[54:55], s[54:55], 12
	s_lshl_b64 s[54:55], s[54:55], 1
	s_andn2_b64 vcc, exec, s[56:57]
	s_waitcnt lgkmcnt(1)
	v_cvt_pk_bf16_f32 v18, v18, v19
	v_cvt_pk_bf16_f32 v19, v20, v21
	s_waitcnt lgkmcnt(0)
	v_cvt_pk_bf16_f32 v20, v22, v23
	v_cvt_pk_bf16_f32 v21, v24, v25
	ds_write_b128 v117, v[18:21] offset:27648
	s_waitcnt lgkmcnt(0)
	s_barrier
	ds_read_b128 v[18:21], v214
	ds_read_b128 v[22:25], v214 offset:2304
	ds_read_b128 v[26:29], v213 offset:64768
	ds_read_b128 v[30:33], v213 offset:37120
	ds_read_b128 v[34:37], v216
	s_waitcnt lgkmcnt(2)
	v_mfma_f32_16x16x32_bf16 v[18:21], v[18:21], v[26:29], 0
	v_mfma_f32_16x16x32_bf16 v[22:25], v[22:25], v[26:29], 0
	ds_read_b128 v[26:29], v217 offset:2304
	ds_read_b128 v[38:41], v215 offset:64768
	ds_read_b128 v[46:49], v215 offset:37120
	s_waitcnt lgkmcnt(1)
	v_mfma_f32_16x16x32_bf16 v[18:21], v[34:37], v[38:41], v[18:21]
	ds_read_b128 v[34:37], v167
	v_mfma_f32_16x16x32_bf16 v[22:25], v[26:29], v[38:41], v[22:25]
	ds_read_b128 v[26:29], v167 offset:2304
	ds_read_b128 v[38:41], v168
	s_nop 3
	v_cvt_pk_bf16_f32 v18, v18, v19
	s_waitcnt lgkmcnt(2)
	v_mfma_f32_16x16x32_bf16 v[34:37], v[34:37], v[30:33], 0
	v_cvt_pk_bf16_f32 v19, v20, v21
	s_waitcnt lgkmcnt(1)
	v_mfma_f32_16x16x32_bf16 v[26:29], v[26:29], v[30:33], 0
	ds_read_b128 v[30:33], v169 offset:2304
	s_waitcnt lgkmcnt(1)
	v_mfma_f32_16x16x32_bf16 v[34:37], v[38:41], v[46:49], v[34:37]
	s_waitcnt lgkmcnt(0)
	v_mfma_f32_16x16x32_bf16 v[26:29], v[30:33], v[46:49], v[26:29]
	v_add_u32_e32 v30, 0x100, v233
	s_nop 4
	v_cvt_pk_bf16_f32 v20, v34, v35
	v_cvt_pk_bf16_f32 v21, v36, v37
	ds_write2st64_b64 v30, v[18:19], v[20:21] offset1:18
	v_cvt_pk_bf16_f32 v18, v22, v23
	v_cvt_pk_bf16_f32 v19, v24, v25
	v_cvt_pk_bf16_f32 v20, v26, v27
	v_cvt_pk_bf16_f32 v21, v28, v29
	v_add_u32_e32 v22, 0x100, v239
	ds_write2st64_b64 v22, v[18:19], v[20:21] offset1:18
	s_waitcnt lgkmcnt(0)
	s_barrier
	ds_read_b128 v[18:21], v167
	ds_read_b128 v[22:25], v167 offset:2304
	ds_read_b128 v[26:29], v187 offset:256
	ds_read_b128 v[30:33], v187 offset:320
	ds_read_b128 v[34:37], v168
	s_waitcnt lgkmcnt(2)
	v_mfma_f32_16x16x32_bf16 v[18:21], v[18:21], v[26:29], 0
	v_mfma_f32_16x16x32_bf16 v[22:25], v[22:25], v[26:29], 0
	ds_read_b128 v[26:29], v169 offset:2304
	s_waitcnt lgkmcnt(1)
	v_mfma_f32_16x16x32_bf16 v[18:21], v[34:37], v[30:33], v[18:21]
	s_waitcnt lgkmcnt(0)
	v_mfma_f32_16x16x32_bf16 v[22:25], v[26:29], v[30:33], v[22:25]
	s_nop 5
	v_cvt_pk_bf16_f32 v18, v18, v19
	v_cvt_pk_bf16_f32 v19, v20, v21
	v_add_u32_e32 v20, v221, v120
	ds_write_b64 v20, v[18:19] offset:18688
	v_cvt_pk_bf16_f32 v18, v22, v23
	v_cvt_pk_bf16_f32 v19, v24, v25
	ds_write_b64 v251, v[18:19] offset:18688
	s_waitcnt lgkmcnt(0)
	s_barrier
; __device__ __forceinline__ unsigned pk2(float lo, float hi) { f32x2_t v = {lo, hi}; bf16x2_t b = __builtin_convertvector(v, bf16x2_t); return __builtin_bit_cast(unsigned, b); }
; __device__ __forceinline__ float bflo(unsigned v) { return __uint_as_float(v << 16); }
; __device__ __forceinline__ float bfhi(unsigned v) { return __uint_as_float(v & 0xffff0000u); }
; __device__ void rwkv_prep_item(const Params& p, char* lds_, int item, PrepRaw& raw, int next_item) {
;     ...
;   {
;     f32x4 pp[2], qt[2], ry[2], y0[2]; zero2(pp); zero2(qt); zero2(ry); zero2(y0);
;     mm_nt<true, false>(BT, WT, pp, wave, lane);
;     mm_nt<false, true>(U0T, BT, qt, wave, lane); mm_nt<true, true>(VT, KT, qt, wave, lane);
;     mm_nt(MRB, WT, ry, wave, lane);
;     ...
;     mm_nt<false, true>(MRK, VT, y0, wave, lane);
;     ...
;     mm_nt(MRB, U0T, y0, wave, lane);
;     ...
;     mm_nt(MRB, X1T, y0, wave, lane);
;     ...
;     mm_nt(MRB, VT, y0, wave, lane);
;     ...
;     mm_nt(MRK, U0T, y0, wave, lane);
;     ...
;     mm_nt(MRB, U0T, y0, wave, lane); mm_nt<false, true>(MRK, VT, y0, wave, lane);
;     ...
;     const float gci = gC[mi];
; #pragma unroll
;     for (int jj = 0; jj < 2; ++jj) {
;       const int jt = jt0 + jj, j0 = jt * 16 + 4 * mg;
;       float pv[4];
; #pragma unroll
;       for (int e = 0; e < 4; ++e) pv[e] = gci * (pp[jj][e] + ((j0 + e) == mi ? 1.f : 0.f));
;       u32x2 w; w.x = pk2(pv[0], pv[1]); w.y = pk2(pv[2], pv[3]);
;       *(u32x2*)(p.Pm + (size_t)item * 4096 + mi * 64 + (jt >> 1) * 32 + 8 * mg + 4 * (jt & 1)) = w;
;       const f32x4 gj = *(const f32x4*)(gC + j0);
;       { u32x2 qw; qw.x = pk2(qt[jj][0] * gj[0], qt[jj][1] * gj[1]); qw.y = pk2(qt[jj][2] * gj[2], qt[jj][3] * gj[3]);
;         *(u32x2*)(p.QT + (size_t)item * 4096 + mi * 64 + j0) = qw; }
;       const u32x2 rw = *(const u32x2*)(Rt + mi * LD + j0);
;       w.x = pk2(ry[jj][0] + bflo(rw.x), ry[jj][1] + bfhi(rw.x)); w.y = pk2(ry[jj][2] + bflo(rw.y), ry[jj][3] + bfhi(rw.y));
;       *(u32x2*)(p.Ry + (size_t)item * 4096 + mi * 64 + j0) = w;
;     ...
;       { const u32x2 dw = *(const u32x2*)(DBG_DUMP_SRC + mi * LD + j0); y0[jj][0] = bflo(dw.x); y0[jj][1] = bfhi(dw.x); y0[jj][2] = bflo(dw.y); y0[jj][3] = bfhi(dw.y); }
;     ...
;       { u32x2 yw; yw.x = pk2(y0[jj][0], y0[jj][1]); yw.y = pk2(y0[jj][2], y0[jj][3]);
;         *(u32x2*)(p.Y0 + (size_t)item * 4096 + mi * 64 + j0) = yw; }
;     }
	ds_read_b128 v[18:21], v188 offset:9472
	ds_read_b128 v[22:25], v213 offset:46336
	ds_read_b128 v[26:29], v188 offset:9536
	ds_read_b128 v[30:33], v213 offset:64768
	ds_read_b128 v[38:41], v188 offset:11776
	ds_read_b128 v[46:49], v188 offset:11840
	ds_read_b128 v[50:53], v215 offset:46336
	ds_read_b128 v[54:57], v215 offset:64768
	ds_read_b128 v[58:61], v222 offset:46336
	s_waitcnt lgkmcnt(7)
	v_mfma_f32_16x16x32_bf16 v[34:37], v[18:21], v[22:25], 0
	s_waitcnt lgkmcnt(4)
	v_mfma_f32_16x16x32_bf16 v[22:25], v[38:41], v[22:25], 0
	s_waitcnt lgkmcnt(2)
	v_mfma_f32_16x16x32_bf16 v[34:37], v[26:29], v[50:53], v[34:37]
	v_mfma_f32_16x16x32_bf16 v[22:25], v[46:49], v[50:53], v[22:25]
	ds_read_b128 v[50:53], v187 offset:18688
	ds_read_b128 v[62:65], v187 offset:18752
	ds_read_b128 v[66:69], v222 offset:55552
	ds_read_b128 v[70:73], v224 offset:46336
	ds_read_b128 v[74:77], v222 offset:64768
	s_nop 1
	v_pk_add_f32 v[34:35], v[122:123], v[34:35]
	s_waitcnt lgkmcnt(4)
	v_mfma_f32_16x16x32_bf16 v[58:61], v[58:61], v[50:53], 0
	v_add_f32_e64 v36, v124, v36
	v_add_f32_e64 v37, v125, v37
	v_pk_add_f32 v[24:25], v[128:129], v[24:25]
	s_waitcnt lgkmcnt(1)
	v_mfma_f32_16x16x32_bf16 v[50:53], v[70:73], v[50:53], 0
	ds_read_b128 v[70:73], v225 offset:46336
	ds_read_b128 v[78:81], v225 offset:55552
	s_waitcnt lgkmcnt(1)
	v_mfma_f32_16x16x32_bf16 v[58:61], v[70:73], v[62:65], v[58:61]
	ds_read_b128 v[70:73], v226 offset:46336
	ds_read_b128 v[82:85], v225 offset:64768
	s_waitcnt lgkmcnt(1)
	v_mfma_f32_16x16x32_bf16 v[50:53], v[70:73], v[62:65], v[50:53]
	v_mfma_f32_16x16x32_bf16 v[58:61], v[66:69], v[30:33], v[58:61]
	ds_read_b128 v[62:65], v224 offset:55552
	ds_read_b128 v[66:69], v224 offset:64768
	s_waitcnt lgkmcnt(1)
	v_mfma_f32_16x16x32_bf16 v[30:33], v[62:65], v[30:33], v[50:53]
	v_mfma_f32_16x16x32_bf16 v[50:53], v[78:81], v[54:57], v[58:61]
	s_nop 2
	ds_read_b128 v[58:61], v226 offset:55552
	ds_read_b128 v[62:65], v226 offset:64768
	s_waitcnt lgkmcnt(1)
	v_mfma_f32_16x16x32_bf16 v[30:33], v[58:61], v[54:57], v[30:33]
	ds_read_b128 v[54:57], v166
	ds_read_b128 v[58:61], v166 offset:64
	ds_read_b128 v[70:73], v188 offset:20992
	s_waitcnt lgkmcnt(2)
	v_mfma_f32_16x16x32_bf16 v[18:21], v[18:21], v[54:57], 0
	s_waitcnt lgkmcnt(1)
	v_mfma_f32_16x16x32_bf16 v[18:21], v[26:29], v[58:61], v[18:21]
	ds_read_b128 v[26:29], v188 offset:18688
	v_mfma_f32_16x16x32_bf16 v[38:41], v[38:41], v[54:57], 0
	s_waitcnt lgkmcnt(0)
	v_mfma_f32_16x16x32_bf16 v[26:29], v[26:29], v[54:57], 0
	v_mfma_f32_16x16x32_bf16 v[38:41], v[46:49], v[58:61], v[38:41]
	ds_read_b128 v[46:49], v188 offset:18752
	ds_read_b128 v[78:81], v188 offset:21056
	ds_read_b32 v94, v228
	ds_read_b128 v[86:89], v227
	ds_read_b128 v[90:93], v227 offset:64
	s_waitcnt lgkmcnt(2)
	v_pk_mul_f32 v[34:35], v[34:35], v[94:95] op_sel_hi:[1,0]
	v_mfma_f32_16x16x32_bf16 v[26:29], v[46:49], v[58:61], v[26:29]
	ds_read_b128 v[46:49], v234
	v_pk_mul_f32 v[36:37], v[36:37], v[94:95] op_sel_hi:[1,0]
	v_pk_mul_f32 v[24:25], v[24:25], v[94:95] op_sel_hi:[1,0]
	v_mfma_f32_16x16x32_bf16 v[54:57], v[70:73], v[54:57], 0
	ds_read_b64 v[70:71], v233 offset:27904
	s_waitcnt lgkmcnt(1)
	v_pk_mul_f32 v[48:49], v[52:53], v[48:49]
	v_pk_mul_f32 v[46:47], v[50:51], v[46:47]
	v_mfma_f32_16x16x32_bf16 v[26:29], v[74:77], v[86:89], v[26:29]
	v_cvt_pk_bf16_f32 v72, v34, v35
	v_cvt_pk_bf16_f32 v73, v36, v37
	v_cvt_pk_bf16_f32 v46, v46, v47
	v_mfma_f32_16x16x32_bf16 v[34:37], v[78:81], v[58:61], v[54:57]
	v_cvt_pk_bf16_f32 v47, v48, v49
	v_lshl_add_u64 v[48:49], v[142:143], 0, s[54:55]
	s_nop 0
	v_lshl_add_u64 v[54:55], v[140:141], 0, s[54:55]
	global_store_dwordx2 v[54:55], v[72:73], off
	v_mfma_f32_16x16x32_bf16 v[26:29], v[82:85], v[90:93], v[26:29]
	global_store_dwordx2 v[48:49], v[46:47], off
	s_waitcnt lgkmcnt(0)
	v_lshlrev_b32_e32 v46, 16, v70
	v_and_b32_e32 v47, 0xffff0000, v70
	v_pk_add_f32 v[18:19], v[18:19], v[46:47]
	v_lshlrev_b32_e32 v46, 16, v71
	v_and_b32_e32 v47, 0xffff0000, v71
	v_pk_add_f32 v[20:21], v[20:21], v[46:47]
	v_cvt_pk_bf16_f32 v18, v18, v19
	v_cvt_pk_bf16_f32 v19, v20, v21
	v_lshl_add_u64 v[20:21], v[144:145], 0, s[54:55]
	global_store_dwordx2 v[20:21], v[18:19], off
	v_cvt_pk_bf16_f32 v18, v26, v27
	v_cvt_pk_bf16_f32 v19, v28, v29
	v_lshl_add_u64 v[20:21], v[146:147], 0, s[54:55]
	global_store_dwordx2 v[20:21], v[18:19], off
	v_pk_add_f32 v[18:19], v[126:127], v[22:23]
	ds_read_b64 v[56:57], v239 offset:27904
	v_pk_mul_f32 v[22:23], v[18:19], v[94:95] op_sel_hi:[1,0]
	ds_read_b128 v[18:21], v243
	v_mfma_f32_16x16x32_bf16 v[34:37], v[66:69], v[86:89], v[34:37]
	v_cvt_pk_bf16_f32 v22, v22, v23
	v_cvt_pk_bf16_f32 v23, v24, v25
	global_store_dwordx2 v[54:55], v[22:23], off offset:8
	s_waitcnt lgkmcnt(0)
	v_pk_mul_f32 v[20:21], v[32:33], v[20:21]
	v_pk_mul_f32 v[18:19], v[30:31], v[18:19]
	v_mfma_f32_16x16x32_bf16 v[34:37], v[62:65], v[90:93], v[34:37]
	v_cvt_pk_bf16_f32 v18, v18, v19
	v_cvt_pk_bf16_f32 v19, v20, v21
	v_lshl_add_u64 v[20:21], v[148:149], 0, s[54:55]
	global_store_dwordx2 v[20:21], v[18:19], off
	v_lshlrev_b32_e32 v18, 16, v56
	v_and_b32_e32 v19, 0xffff0000, v56
	v_lshlrev_b32_e32 v20, 16, v57
	v_and_b32_e32 v21, 0xffff0000, v57
	v_pk_add_f32 v[18:19], v[38:39], v[18:19]
	v_pk_add_f32 v[20:21], v[40:41], v[20:21]
	v_cvt_pk_bf16_f32 v18, v18, v19
	v_cvt_pk_bf16_f32 v19, v20, v21
	v_lshl_add_u64 v[20:21], v[150:151], 0, s[54:55]
	global_store_dwordx2 v[20:21], v[18:19], off
	v_cvt_pk_bf16_f32 v18, v34, v35
	v_cvt_pk_bf16_f32 v19, v36, v37
	v_lshl_add_u64 v[20:21], v[152:153], 0, s[54:55]
	global_store_dwordx2 v[20:21], v[18:19], off
	s_waitcnt vmcnt(11)
	v_mov_b64_e32 v[18:19], v[42:43]
	s_mov_b32 s54, s90
	v_mov_b64_e32 v[20:21], v[44:45]
	s_cbranch_vccz .LBB0_329

; __device__ __forceinline__ float fsigmoid(float x) { return __builtin_amdgcn_rcpf(1.f + fexp(-x)); }
; __device__ void rwkv_prep_item(const Params& p, char* lds_, int item, PrepRaw& raw, int next_item) {
;     ...
;       const float zw = Zw[t * 68 + cg8 + e] + pdb[e >> 2][e & 3];
;       const float za = Za[t * 68 + cg8 + e] + pib[e >> 2][e & 3];
;       lw[e] = -0.6065306597126334f * fsigmoid(zw);
;     ...
;   __syncthreads();
; #pragma unroll
;   for (int e = 0; e < 8; ++e) G[t * 68 + cg8 + e] = lw[e];
;   __syncthreads();
;   {
;     const int d = tid & 63, seg = tid >> 6;
;     float s = 0.f;
; #pragma unroll
;     for (int q = 0; q < 8; ++q) s += G[(seg * 8 + q) * 68 + d];
;     Za[seg * 64 + d] = s;
;   }
;   __syncthreads();
;   {
;     const int d = tid & 63, seg = tid >> 6;
;     float pre = 0.f;
;     for (int q = 0; q < seg; ++q) pre += Za[q * 64 + d];
.LBB0_293:
	v_add_f32_e32 v34, v34, v58
	v_mul_f32_e32 v34, 0xbfb8aa3b, v34
	v_add_f32_e32 v35, v35, v59
	v_exp_f32_e32 v34, v34
	v_mul_f32_e32 v35, 0xbfb8aa3b, v35
	v_exp_f32_e32 v35, v35
	v_add_f32_e32 v38, v38, v74
	v_add_f32_e32 v34, 1.0, v34
	v_rcp_f32_e32 v58, v34
	v_add_f32_e32 v34, 1.0, v35
	v_add_f32_e32 v35, v36, v60
	v_add_f32_e32 v39, v39, v75
	v_add_f32_e32 v40, v40, v76
	v_add_f32_e32 v41, v41, v77
	v_mul_f32_e32 v35, 0xbfb8aa3b, v35
	v_add_f32_e32 v36, v37, v61
	v_mul_f32_e32 v38, 0xbfb8aa3b, v38
	v_mul_f32_e32 v39, 0xbfb8aa3b, v39
	v_mul_f32_e32 v40, 0xbfb8aa3b, v40
	v_mul_f32_e32 v41, 0xbfb8aa3b, v41
	v_exp_f32_e32 v35, v35
	v_mul_f32_e32 v36, 0xbfb8aa3b, v36
	v_exp_f32_e32 v38, v38
	v_exp_f32_e32 v39, v39
	v_exp_f32_e32 v40, v40
	v_exp_f32_e32 v41, v41
	v_exp_f32_e32 v36, v36
	v_rcp_f32_e32 v59, v34
	v_add_f32_e32 v34, 1.0, v35
	v_add_f32_e32 v38, 1.0, v38
	v_add_f32_e32 v39, 1.0, v39
	v_add_f32_e32 v40, 1.0, v40
	v_add_f32_e32 v41, 1.0, v41
	v_rcp_f32_e32 v60, v34
	v_add_f32_e32 v34, 1.0, v36
	v_rcp_f32_e32 v38, v38
	v_rcp_f32_e32 v39, v39
	v_rcp_f32_e32 v40, v40
	v_rcp_f32_e32 v41, v41
	v_rcp_f32_e32 v61, v34
	v_pk_mul_f32 v[34:35], v[38:39], s[52:53] op_sel_hi:[1,0]
	v_pk_mul_f32 v[38:39], v[58:59], s[52:53] op_sel_hi:[1,0]
	v_pk_mul_f32 v[36:37], v[40:41], s[52:53] op_sel_hi:[1,0]
	v_pk_mul_f32 v[40:41], v[60:61], s[52:53] op_sel_hi:[1,0]
	s_waitcnt lgkmcnt(0)
	ds_write_b128 v181, v[34:37]
	ds_write_b128 v181, v[38:41] offset:16
	s_waitcnt lgkmcnt(0)
	s_barrier
	ds_read2_b32 v[60:61], v252 offset1:68
	ds_read2_b32 v[74:75], v252 offset0:136 offset1:204
	v_add_u32_e32 v58, 0x400, v252
	ds_read2_b32 v[76:77], v58 offset0:16 offset1:84
	v_mov_b32_e32 v59, 0
	s_waitcnt lgkmcnt(2)
	v_add_f32_e32 v60, 0, v60
	v_add_f32_e32 v84, v60, v61
	ds_read2_b32 v[60:61], v58 offset0:152 offset1:220
	s_waitcnt lgkmcnt(2)
	v_add_f32_e32 v74, v84, v74
	v_add_f32_e32 v74, v74, v75
	s_waitcnt lgkmcnt(1)
	v_add_f32_e32 v74, v74, v76
	v_add_f32_e32 v74, v74, v77
	s_waitcnt lgkmcnt(0)
	v_add_f32_e32 v60, v74, v60
	v_add_f32_e32 v60, v60, v61
	ds_write_b32 v182, v60
	s_waitcnt lgkmcnt(0)
	s_barrier
	s_and_saveexec_b64 s[58:59], s[6:7]
	s_cbranch_execz .LBB0_303
	v_mov_b32_e32 v59, 0
	v_mov_b32_e32 v60, 0
	s_and_saveexec_b64 s[84:85], s[44:45]
	s_cbranch_execz .LBB0_298
	s_mov_b32 s55, 0
	v_mov_b32_e32 v59, 0
	s_mov_b64 s[86:87], 0
	v_mov_b32_e32 v60, v245
